# diff-attention non-diagonal tiles: hand-scheduled fast path (no zero-init, fmamk ALiBi bias, 4-deep LDS fragment pipeline, ds_read_b64 V fragments, exp/cvt under MFMAs)
# speedup vs baseline: 1.0256x; 1.0208x over previous
.LBB0_871:
	s_add_i32 s0, s0, -1
	s_cmp_ge_i32 s0, s52
	s_cselect_b64 s[0:1], -1, 0
	s_mov_b64 s[4:5], -1
	s_and_b64 vcc, exec, s[0:1]
	s_mov_b64 s[40:41], -1
	s_waitcnt lgkmcnt(0)
	s_barrier
	s_cbranch_vccnz .Ldiff_diag
	v_subrev_u32_e32 v0, 63, v240
	v_cvt_f32_i32_e32 v0, v0
	v_mul_f32_e64 v0, -v166, v0
	v_cmp_nlt_f32_e32 vcc, v0, v235
	s_cbranch_vccz .LBB0_878
	v_add_u32_e32 v243, s43, v228
	v_add3_u32 v243, v243, v229, v230
	ds_read_b128 v[2:5], v243
	ds_read_b128 v[6:9], v243 offset:32
	ds_read_b128 v[10:13], v243 offset:64
	ds_read_b128 v[252:255], v243 offset:96
	v_add3_u32 v251, s43, v236, v234
	v_add_u32_e32 v242, s34, v238
	v_cvt_f32_i32_e32 v242, v242
	v_add_u32_e32 v251, 0x4400, v251
	v_fma_f32 v242, v166, v242, -v233
	v_mov_b32_e32 v96, v242
	v_add_f32_e32 v97, v166, v242
	v_fmamk_f32 v98, v166, 0x40000000, v242
	v_fmamk_f32 v99, v166, 0x40400000, v242
	v_fmamk_f32 v100, v166, 0x41000000, v242
	v_fmamk_f32 v101, v166, 0x41100000, v242
	v_fmamk_f32 v102, v166, 0x41200000, v242
	v_fmamk_f32 v103, v166, 0x41300000, v242
	v_fmamk_f32 v104, v166, 0x41800000, v242
	v_fmamk_f32 v105, v166, 0x41880000, v242
	v_fmamk_f32 v106, v166, 0x41900000, v242
	v_fmamk_f32 v107, v166, 0x41980000, v242
	v_fmamk_f32 v108, v166, 0x41c00000, v242
	v_fmamk_f32 v109, v166, 0x41c80000, v242
	v_fmamk_f32 v110, v166, 0x41d00000, v242
	v_fmamk_f32 v111, v166, 0x41d80000, v242
	v_fmamk_f32 v80, v166, 0x42000000, v242
	v_fmamk_f32 v81, v166, 0x42040000, v242
	v_fmamk_f32 v82, v166, 0x42080000, v242
	v_fmamk_f32 v83, v166, 0x420c0000, v242
	v_fmamk_f32 v84, v166, 0x42200000, v242
	v_fmamk_f32 v85, v166, 0x42240000, v242
	v_fmamk_f32 v86, v166, 0x42280000, v242
	v_fmamk_f32 v87, v166, 0x422c0000, v242
	v_fmamk_f32 v88, v166, 0x42400000, v242
	v_fmamk_f32 v89, v166, 0x42440000, v242
	v_fmamk_f32 v90, v166, 0x42480000, v242
	v_fmamk_f32 v91, v166, 0x424c0000, v242
	v_fmamk_f32 v92, v166, 0x42600000, v242
	v_fmamk_f32 v93, v166, 0x42640000, v242
	v_fmamk_f32 v94, v166, 0x42680000, v242
	v_fmamk_f32 v95, v166, 0x426c0000, v242
	s_waitcnt lgkmcnt(3)
	v_mfma_f32_32x32x16_bf16 v[96:111], v[2:5], v[112:115], v[96:111]
	ds_read_b128 v[2:5], v243 offset:8704
	v_lshl_add_u64 v[176:177], v[176:177], 0, s[24:25]
	v_lshl_add_u64 v[178:179], v[178:179], 0, s[26:27]
	s_waitcnt lgkmcnt(3)
	v_mfma_f32_32x32x16_bf16 v[96:111], v[6:9], v[116:119], v[96:111]
	ds_read_b128 v[6:9], v243 offset:8736
	v_lshl_add_u64 v[180:181], v[180:181], 0, s[26:27]
	v_lshl_add_u64 v[182:183], v[182:183], 0, s[26:27]
	s_waitcnt lgkmcnt(3)
	v_mfma_f32_32x32x16_bf16 v[96:111], v[10:13], v[120:123], v[96:111]
	ds_read_b128 v[10:13], v243 offset:8768
	v_lshl_add_u64 v[184:185], v[184:185], 0, s[26:27]
	v_lshl_add_u64 v[186:187], v[186:187], 0, s[24:25]
	s_waitcnt lgkmcnt(3)
	v_mfma_f32_32x32x16_bf16 v[96:111], v[252:255], v[124:127], v[96:111]
	ds_read_b128 v[252:255], v243 offset:8800
	v_lshl_add_u64 v[188:189], v[188:189], 0, s[24:25]
	v_lshl_add_u64 v[190:191], v[190:191], 0, s[24:25]
	s_waitcnt lgkmcnt(3)
	v_mfma_f32_32x32x16_bf16 v[80:95], v[2:5], v[112:115], v[80:95]
	ds_read_b64 v[2:3], v251
	ds_read_b64 v[4:5], v251 offset:16
	s_waitcnt lgkmcnt(4)
	v_mfma_f32_32x32x16_bf16 v[80:95], v[6:9], v[116:119], v[80:95]
	ds_read_b64 v[6:7], v251 offset:4352
	ds_read_b64 v[8:9], v251 offset:4368
	s_waitcnt lgkmcnt(5)
	v_mfma_f32_32x32x16_bf16 v[80:95], v[10:13], v[120:123], v[80:95]
	ds_read_b64 v[10:11], v251 offset:8704
	ds_read_b64 v[12:13], v251 offset:8720
	v_exp_f32_e32 v96, v96
	v_exp_f32_e32 v97, v97
	v_exp_f32_e32 v98, v98
	v_exp_f32_e32 v99, v99
	s_waitcnt lgkmcnt(6)
	v_mfma_f32_32x32x16_bf16 v[80:95], v[252:255], v[124:127], v[80:95]
	ds_read_b64 v[252:253], v251 offset:13056
	ds_read_b64 v[254:255], v251 offset:13072
	v_exp_f32_e32 v100, v100
	v_exp_f32_e32 v101, v101
	v_exp_f32_e32 v102, v102
	v_exp_f32_e32 v103, v103
	v_cvt_pk_bf16_f32 v242, v96, v97
	v_cvt_pk_bf16_f32 v243, v98, v99
	v_cvt_pk_bf16_f32 v244, v100, v101
	v_cvt_pk_bf16_f32 v245, v102, v103
	s_nop 0
	s_waitcnt lgkmcnt(6)
	v_mfma_f32_32x32x16_bf16 v[64:79], v[2:5], v[242:245], v[64:79]
	ds_read_b64 v[2:3], v251 offset:32
	ds_read_b64 v[4:5], v251 offset:48
	v_exp_f32_e32 v104, v104
	v_exp_f32_e32 v105, v105
	v_exp_f32_e32 v106, v106
	v_exp_f32_e32 v107, v107
	v_exp_f32_e32 v108, v108
	s_waitcnt lgkmcnt(6)
	v_mfma_f32_32x32x16_bf16 v[48:63], v[6:9], v[242:245], v[48:63]
	ds_read_b64 v[6:7], v251 offset:4384
	ds_read_b64 v[8:9], v251 offset:4400
	v_exp_f32_e32 v109, v109
	v_exp_f32_e32 v110, v110
	v_exp_f32_e32 v111, v111
	v_cvt_pk_bf16_f32 v246, v104, v105
	v_cvt_pk_bf16_f32 v247, v106, v107
	s_waitcnt lgkmcnt(6)
	v_mfma_f32_32x32x16_bf16 v[32:47], v[10:13], v[242:245], v[32:47]
	ds_read_b64 v[10:11], v251 offset:8736
	ds_read_b64 v[12:13], v251 offset:8752
	v_cvt_pk_bf16_f32 v248, v108, v109
	v_cvt_pk_bf16_f32 v249, v110, v111
	v_add_f32_e32 v96, v96, v97
	v_add_f32_e32 v98, v98, v99
	v_add_f32_e32 v100, v100, v101
	s_waitcnt lgkmcnt(6)
	v_mfma_f32_32x32x16_bf16 v[16:31], v[252:255], v[242:245], v[16:31]
	ds_read_b64 v[252:253], v251 offset:13088
	ds_read_b64 v[254:255], v251 offset:13104
	v_add_f32_e32 v102, v102, v103
	v_add_f32_e32 v96, v96, v98
	v_add_f32_e32 v100, v100, v102
	v_add_f32_e32 v96, v96, v100
	v_add_f32_e32 v239, v239, v96
	s_waitcnt lgkmcnt(6)
	v_mfma_f32_32x32x16_bf16 v[64:79], v[2:5], v[246:249], v[64:79]
	ds_read_b64 v[2:3], v251 offset:64
	ds_read_b64 v[4:5], v251 offset:80
	v_exp_f32_e32 v80, v80
	v_exp_f32_e32 v81, v81
	v_exp_f32_e32 v82, v82
	v_exp_f32_e32 v83, v83
	v_exp_f32_e32 v84, v84
	s_waitcnt lgkmcnt(6)
	v_mfma_f32_32x32x16_bf16 v[48:63], v[6:9], v[246:249], v[48:63]
	ds_read_b64 v[6:7], v251 offset:4416
	ds_read_b64 v[8:9], v251 offset:4432
	v_exp_f32_e32 v85, v85
	v_exp_f32_e32 v86, v86
	v_exp_f32_e32 v87, v87
	v_cvt_pk_bf16_f32 v242, v80, v81
	v_cvt_pk_bf16_f32 v243, v82, v83
	s_waitcnt lgkmcnt(6)
	v_mfma_f32_32x32x16_bf16 v[32:47], v[10:13], v[246:249], v[32:47]
	ds_read_b64 v[10:11], v251 offset:8768
	ds_read_b64 v[12:13], v251 offset:8784
	v_cvt_pk_bf16_f32 v244, v84, v85
	v_cvt_pk_bf16_f32 v245, v86, v87
	v_add_f32_e32 v104, v104, v105
	v_add_f32_e32 v106, v106, v107
	v_add_f32_e32 v108, v108, v109
	s_waitcnt lgkmcnt(6)
	v_mfma_f32_32x32x16_bf16 v[16:31], v[252:255], v[246:249], v[16:31]
	ds_read_b64 v[252:253], v251 offset:13120
	ds_read_b64 v[254:255], v251 offset:13136
	v_add_f32_e32 v110, v110, v111
	v_add_f32_e32 v104, v104, v106
	v_add_f32_e32 v108, v108, v110
	v_add_f32_e32 v104, v104, v108
	v_add_f32_e32 v239, v239, v104
	s_waitcnt lgkmcnt(6)
	v_mfma_f32_32x32x16_bf16 v[64:79], v[2:5], v[242:245], v[64:79]
	ds_read_b64 v[2:3], v251 offset:96
	ds_read_b64 v[4:5], v251 offset:112
	v_exp_f32_e32 v88, v88
	v_exp_f32_e32 v89, v89
	v_exp_f32_e32 v90, v90
	v_exp_f32_e32 v91, v91
	v_exp_f32_e32 v92, v92
	s_waitcnt lgkmcnt(6)
	v_mfma_f32_32x32x16_bf16 v[48:63], v[6:9], v[242:245], v[48:63]
	ds_read_b64 v[6:7], v251 offset:4448
	ds_read_b64 v[8:9], v251 offset:4464
	v_exp_f32_e32 v93, v93
	v_exp_f32_e32 v94, v94
	v_exp_f32_e32 v95, v95
	v_cvt_pk_bf16_f32 v246, v88, v89
	v_cvt_pk_bf16_f32 v247, v90, v91
	s_waitcnt lgkmcnt(6)
	v_mfma_f32_32x32x16_bf16 v[32:47], v[10:13], v[242:245], v[32:47]
	ds_read_b64 v[10:11], v251 offset:8800
	ds_read_b64 v[12:13], v251 offset:8816
	v_cvt_pk_bf16_f32 v248, v92, v93
	v_cvt_pk_bf16_f32 v249, v94, v95
	v_add_f32_e32 v80, v80, v81
	v_add_f32_e32 v82, v82, v83
	v_add_f32_e32 v84, v84, v85
	s_waitcnt lgkmcnt(6)
	v_mfma_f32_32x32x16_bf16 v[16:31], v[252:255], v[242:245], v[16:31]
	ds_read_b64 v[252:253], v251 offset:13152
	ds_read_b64 v[254:255], v251 offset:13168
	v_add_f32_e32 v86, v86, v87
	v_add_f32_e32 v80, v80, v82
	v_add_f32_e32 v84, v84, v86
	v_add_f32_e32 v80, v80, v84
	v_add_f32_e32 v239, v239, v80
	s_waitcnt lgkmcnt(6)
	v_mfma_f32_32x32x16_bf16 v[64:79], v[2:5], v[246:249], v[64:79]
	v_add_f32_e32 v88, v88, v89
	v_add_f32_e32 v90, v90, v91
	v_add_f32_e32 v92, v92, v93
	v_add_f32_e32 v94, v94, v95
	s_waitcnt lgkmcnt(4)
	v_mfma_f32_32x32x16_bf16 v[48:63], v[6:9], v[246:249], v[48:63]
	v_add_f32_e32 v88, v88, v90
	v_add_f32_e32 v92, v92, v94
	v_add_f32_e32 v88, v88, v92
	v_add_f32_e32 v239, v239, v88
	s_waitcnt lgkmcnt(2)
	v_mfma_f32_32x32x16_bf16 v[32:47], v[10:13], v[246:249], v[32:47]
	v_add_u32_e32 v232, -1, v232
	s_xor_b32 s42, s42, 1
	s_sub_i32 s6, s6, 64
	v_subrev_u32_e32 v238, 64, v238
	s_waitcnt lgkmcnt(0)
	v_mfma_f32_32x32x16_bf16 v[16:31], v[252:255], v[246:249], v[16:31]
	v_subrev_u32_e32 v241, 64, v241
	v_add_u32_e32 v240, 64, v240
	v_cmp_gt_u32_e64 s[4:5], 2, v232
	s_and_b64 vcc, exec, s[4:5]
	s_cbranch_vccz .LBB0_869
	s_branch .LBB0_879
.Ldiff_diag:
	v_mov_b32_e32 v111, 0
	v_mov_b32_e32 v110, 0
	v_mov_b32_e32 v109, 0
	v_mov_b32_e32 v108, 0
	v_mov_b32_e32 v107, 0
	v_mov_b32_e32 v106, 0
	v_mov_b32_e32 v105, 0
	v_mov_b32_e32 v104, 0
	v_mov_b32_e32 v103, 0
	v_mov_b32_e32 v102, 0
	v_mov_b32_e32 v101, 0
	v_mov_b32_e32 v100, 0
	v_mov_b32_e32 v99, 0
	v_mov_b32_e32 v98, 0
	v_mov_b32_e32 v97, 0
	v_mov_b32_e32 v96, 0
	v_mov_b32_e32 v95, 0
	v_mov_b32_e32 v94, 0
	v_mov_b32_e32 v93, 0
	v_mov_b32_e32 v92, 0
	v_mov_b32_e32 v91, 0
	v_mov_b32_e32 v90, 0
	v_mov_b32_e32 v89, 0
	v_mov_b32_e32 v88, 0
	v_mov_b32_e32 v87, 0
	v_mov_b32_e32 v86, 0
	v_mov_b32_e32 v85, 0
	v_mov_b32_e32 v84, 0
	v_mov_b32_e32 v83, 0
	v_mov_b32_e32 v82, 0
	v_mov_b32_e32 v81, 0
	v_mov_b32_e32 v80, 0

	.amdhsa_kernel _Z4megaILin1EEv6Params
		.amdhsa_group_segment_fixed_size 73748
		.amdhsa_private_segment_fixed_size 0
		.amdhsa_kernarg_size 440
		.amdhsa_user_sgpr_count 2
		.amdhsa_user_sgpr_dispatch_ptr 0
		.amdhsa_user_sgpr_queue_ptr 0
		.amdhsa_user_sgpr_kernarg_segment_ptr 1
		.amdhsa_user_sgpr_dispatch_id 0
		.amdhsa_user_sgpr_kernarg_preload_length 0
		.amdhsa_user_sgpr_kernarg_preload_offset 0
		.amdhsa_user_sgpr_private_segment_size 0
		.amdhsa_uses_dynamic_stack 0
		.amdhsa_enable_private_segment 0
		.amdhsa_system_sgpr_workgroup_id_x 1
		.amdhsa_system_sgpr_workgroup_id_y 0
		.amdhsa_system_sgpr_workgroup_id_z 0
		.amdhsa_system_sgpr_workgroup_info 0
		.amdhsa_system_vgpr_workitem_id 2
		.amdhsa_next_free_vgpr 256
		.amdhsa_next_free_sgpr 98
		.amdhsa_accum_offset 256
		.amdhsa_reserve_vcc 1
		.amdhsa_float_round_mode_32 0
		.amdhsa_float_round_mode_16_64 0
		.amdhsa_float_denorm_mode_32 3
		.amdhsa_float_denorm_mode_16_64 3
		.amdhsa_dx10_clamp 1
		.amdhsa_ieee_mode 1
		.amdhsa_fp16_overflow 0
		.amdhsa_tg_split 0
		.amdhsa_exception_fp_ieee_invalid_op 0
		.amdhsa_exception_fp_denorm_src 0
		.amdhsa_exception_fp_ieee_div_zero 0
		.amdhsa_exception_fp_ieee_overflow 0
		.amdhsa_exception_fp_ieee_underflow 0
		.amdhsa_exception_fp_ieee_inexact 0
		.amdhsa_exception_int_div_zero 0
	.end_amdhsa_kernel

.Lfunc_end0:
	.size	_Z4megaILin1EEv6Params, .Lfunc_end0-_Z4megaILin1EEv6Params
	.set _Z4megaILin1EEv6Params.num_vgpr, 256
	.set _Z4megaILin1EEv6Params.num_agpr, 0
	.set _Z4megaILin1EEv6Params.numbered_sgpr, 98
	.set _Z4megaILin1EEv6Params.num_named_barrier, 0
	.set _Z4megaILin1EEv6Params.private_seg_size, 0
	.set _Z4megaILin1EEv6Params.uses_vcc, 1
	.set _Z4megaILin1EEv6Params.uses_flat_scratch, 0
	.set _Z4megaILin1EEv6Params.has_dyn_sized_stack, 0
	.set _Z4megaILin1EEv6Params.has_recursion, 0
	.set _Z4megaILin1EEv6Params.has_indirect_call, 0

amdhsa.kernels:
  - .agpr_count:     0
    .args:
      - .offset:         0
        .size:           184
        .value_kind:     by_value
      - .offset:         184
        .size:           4
        .value_kind:     hidden_block_count_x
      - .offset:         188
        .size:           4
        .value_kind:     hidden_block_count_y
      - .offset:         192
        .size:           4
        .value_kind:     hidden_block_count_z
      - .offset:         196
        .size:           2
        .value_kind:     hidden_group_size_x
      - .offset:         198
        .size:           2
        .value_kind:     hidden_group_size_y
      - .offset:         200
        .size:           2
        .value_kind:     hidden_group_size_z
      - .offset:         202
        .size:           2
        .value_kind:     hidden_remainder_x
      - .offset:         204
        .size:           2
        .value_kind:     hidden_remainder_y
      - .offset:         206
        .size:           2
        .value_kind:     hidden_remainder_z
      - .offset:         224
        .size:           8
        .value_kind:     hidden_global_offset_x
      - .offset:         232
        .size:           8
        .value_kind:     hidden_global_offset_y
      - .offset:         240
        .size:           8
        .value_kind:     hidden_global_offset_z
      - .offset:         248
        .size:           2
        .value_kind:     hidden_grid_dims
      - .offset:         272
        .size:           8
        .value_kind:     hidden_multigrid_sync_arg
    .group_segment_fixed_size: 73748
    .kernarg_segment_align: 8
    .kernarg_segment_size: 440
    .language:       OpenCL C
    .language_version:
      - 2
      - 0
    .max_flat_workgroup_size: 256
    .name:           _Z4megaILin1EEv6Params
    .private_segment_fixed_size: 0
    .sgpr_count:     104
    .sgpr_spill_count: 20
    .symbol:         _Z4megaILin1EEv6Params.kd
    .uniform_work_group_size: 1
    .uses_dynamic_stack: false
    .vgpr_count:     256
    .vgpr_spill_count: 0
    .wavefront_size: 64
